# gMLP mixer unit dealing: t-block index XOR 2 on each wave's second unit so every wave gets one short (1 s-half) and one long (2 s-half) unit
# speedup vs baseline: 1.0177x; 1.0011x over previous
.LBB0_222:
	s_and_b64 vcc, exec, s[2:3]
	s_cbranch_vccz .LBB0_214
	s_mul_hi_i32 s2, s49, 0x2aaaaaab
	s_lshr_b32 s3, s2, 31
	s_ashr_i32 s2, s2, 2
	s_add_i32 s7, s2, s3
	s_mul_i32 s2, s7, 24
	s_sub_i32 s2, s49, s2
	s_ashr_i32 s8, s2, 2
	s_and_b32 s50, s2, 3
	s_lshr_b32 s3, s49, 10
	s_and_b32 s3, s3, 2
	s_xor_b32 s50, s50, s3
	s_and_b32 s2, s7, 63
	s_lshl_b32 s3, s7, 7
	s_lshl_b32 s2, s2, 7
	s_and_b32 s3, s3, 0xffffe000
	s_or_b32 s6, s3, s2
	s_load_dwordx4 s[40:43], s[0:1], 0x70
	s_load_dwordx2 s[2:3], s[0:1], 0x80
	s_mul_i32 s16, s75, 6
	s_add_i32 s24, s8, s16
	s_ashr_i32 s25, s24, 31
	s_lshl_b64 s[16:17], s[24:25], 16
	s_waitcnt lgkmcnt(0)
	s_add_u32 s34, s42, s16
	s_addc_u32 s35, s43, s17
	s_lshl_b32 s16, s8, 7
	s_ashr_i32 s17, s16, 31
	s_mul_hi_i32 s8, s7, 0x300
	s_mulk_i32 s7, 0x300
	s_add_u32 s38, s7, s16
	s_addc_u32 s39, s8, s17
	s_lshl_b64 s[38:39], s[38:39], 8
	s_add_u32 s38, s12, s38
	s_addc_u32 s39, s13, s39
	s_ashr_i32 s7, s6, 31
	s_lshl_b64 s[42:43], s[6:7], 3
	s_add_u32 s42, s45, s42
	s_waitcnt vmcnt(0)
	v_lshlrev_b32_e32 v0, 1, v207
	s_addc_u32 s43, s46, s43
	v_ashrrev_i32_e32 v1, 31, v0
	v_lshl_add_u64 v[0:1], v[0:1], 3, s[42:43]
	global_load_dwordx4 v[0:3], v[0:1], off
	v_lshlrev_b64 v[4:5], 8, v[148:149]
	v_lshlrev_b32_e32 v10, 4, v207
	v_and_b32_e32 v158, 0x70, v10
	v_lshl_add_u64 v[4:5], s[38:39], 0, v[4:5]
	v_lshl_add_u64 v[150:151], v[4:5], 0, v[158:159]
	v_add_co_u32_e32 v4, vcc, s68, v150
	global_load_dwordx4 v[68:71], v[150:151], off
	global_load_dwordx4 v[64:67], v[150:151], off offset:2048
	v_addc_co_u32_e32 v5, vcc, 0, v151, vcc
	v_add_co_u32_e32 v6, vcc, s23, v150
	v_ashrrev_i32_e32 v213, 4, v207
	s_nop 0
	v_addc_co_u32_e32 v7, vcc, 0, v151, vcc
	v_add_co_u32_e32 v8, vcc, s53, v150
	s_lshl_b32 s38, s50, 5
	s_nop 0
	v_addc_co_u32_e32 v9, vcc, 0, v151, vcc
	global_load_dwordx4 v[92:95], v[8:9], off offset:-4096
	global_load_dwordx4 v[80:83], v[8:9], off
	global_load_dwordx4 v[72:75], v[8:9], off offset:2048
	global_load_dwordx4 v[88:91], v[6:7], off offset:2048
	global_load_dwordx4 v[76:79], v[4:5], off
	v_add_u32_e32 v148, s38, v213
	global_load_dwordx4 v[84:87], v[4:5], off offset:2048
	v_lshlrev_b32_e32 v4, 7, v148
	v_and_b32_e32 v149, 15, v207
	v_ashrrev_i32_e32 v5, 31, v4
	v_lshlrev_b32_e32 v158, 4, v149
	v_lshl_add_u64 v[4:5], v[4:5], 2, s[34:35]
	v_lshl_add_u64 v[152:153], v[4:5], 0, v[158:159]
	v_add_co_u32_e32 v4, vcc, s23, v152
	v_lshl_add_u32 v11, v207, 3, s55
	s_nop 0
	v_addc_co_u32_e32 v5, vcc, 0, v153, vcc
	v_add_co_u32_e32 v6, vcc, s53, v152
	s_mov_b64 s[34:35], 0x1080
	s_nop 0
	v_addc_co_u32_e32 v7, vcc, 0, v153, vcc
	v_lshl_add_u64 v[154:155], v[150:151], 0, s[34:35]
	s_mov_b64 s[34:35], 0x1880
	v_add_u32_e32 v205, 4, v213
	v_add_u32_e32 v201, 12, v213
	v_add_u32_e32 v199, 20, v213
	v_add_u32_e32 v147, 28, v213
	v_add_co_u32_e32 v244, vcc, s68, v152
	s_nop 1
	v_addc_co_u32_e32 v245, vcc, 0, v153, vcc
	global_load_dwordx4 v[96:99], v[152:153], off
	global_load_dwordx4 v[100:103], v[152:153], off offset:2048
	global_load_dwordx4 v[104:107], v[6:7], off
	global_load_dwordx4 v[112:115], v[6:7], off offset:2048
	global_load_dwordx4 v[108:111], v[4:5], off offset:2048
	global_load_dwordx4 v[120:123], v[244:245], off
	global_load_dwordx4 v[116:119], v[6:7], off offset:-4096
	global_load_dwordx4 v[124:127], v[244:245], off offset:2048
	v_add_u32_e32 v22, 4, v212
	v_add_u32_e32 v23, 5, v212
	v_xor_b32_e32 v14, v201, v207
	v_xor_b32_e32 v17, v199, v207
	v_xor_b32_e32 v19, v147, v207
	v_xor_b32_e32 v20, v212, v207
	v_bitop3_b32 v21, v212, v207, 1 bitop3:0x36
	v_xor_b32_e32 v22, v22, v207
	v_xor_b32_e32 v23, v23, v207
	v_xor_b32_e32 v28, v193, v206
	v_xor_b32_e32 v30, v209, v206
	v_xor_b32_e32 v31, v208, v206
	v_add_u32_e32 v202, 8, v213
	v_lshlrev_b32_e32 v14, 4, v14
	v_add_u32_e32 v200, 16, v213
	v_lshlrev_b32_e32 v17, 4, v17
	v_add_u32_e32 v145, 24, v213
	v_lshlrev_b32_e32 v19, 4, v19
	v_lshlrev_b32_e32 v20, 4, v20
	v_lshlrev_b32_e32 v21, 4, v21
	v_lshlrev_b32_e32 v22, 4, v22
	v_lshlrev_b32_e32 v23, 4, v23
	v_lshlrev_b32_e32 v28, 4, v28
	v_lshlrev_b32_e32 v30, 4, v30
	v_lshlrev_b32_e32 v31, 4, v31
	s_mov_b32 s8, 0
	s_cmp_lt_u32 s50, 2
	v_and_b32_e32 v14, 0x70, v14
	v_and_b32_e32 v17, 0x70, v17
	v_and_b32_e32 v19, 0x70, v19
	v_and_b32_e32 v20, 0x70, v20
	v_and_b32_e32 v21, 0x70, v21
	v_and_b32_e32 v22, 0x70, v22
	v_and_b32_e32 v23, 0x70, v23
	s_waitcnt vmcnt(16)
	v_xor_b32_e32 v8, v0, v1
	v_xor_b32_e32 v12, v2, v3
	v_ffbh_i32_e32 v9, v1
	v_ffbh_i32_e32 v13, v3
	v_ashrrev_i32_e32 v8, 31, v8
	v_ashrrev_i32_e32 v12, 31, v12
	v_add_u32_e32 v9, -1, v9
	v_add_u32_e32 v13, -1, v13
	v_add_u32_e32 v8, 32, v8
	v_add_u32_e32 v12, 32, v12
	v_min_u32_e32 v8, v9, v8
	v_min_u32_e32 v9, v13, v12
	v_lshlrev_b64 v[0:1], v8, v[0:1]
	v_lshlrev_b64 v[2:3], v9, v[2:3]
	v_min_u32_e32 v0, 1, v0
	v_min_u32_e32 v2, 1, v2
	v_or_b32_e32 v0, v1, v0
	v_or_b32_e32 v1, v3, v2
	v_cvt_f32_i32_e32 v0, v0
	v_cvt_f32_i32_e32 v1, v1
	v_sub_u32_e32 v2, 32, v8
	v_sub_u32_e32 v3, 32, v9
	v_ldexp_f32 v0, v0, v2
	v_ldexp_f32 v1, v1, v3
	v_mul_f32_e32 v0, 0x35800000, v0
	v_mul_f32_e32 v1, 0x35800000, v1
	v_fmamk_f32 v0, v0, 0x3aaaaaab, v195
	v_fmamk_f32 v1, v1, 0x3aaaaaab, v195
	v_rsq_f32_e32 v0, v0
	v_rsq_f32_e32 v1, v1
	v_add_co_u32_e32 v2, vcc, s68, v152
	v_xor_b32_e32 v9, v213, v207
	ds_write_b64 v11, v[0:1]
	s_waitcnt lgkmcnt(0)
	v_addc_co_u32_e32 v3, vcc, 0, v153, vcc
	v_xor_b32_e32 v3, v168, v207
	v_lshl_add_u64 v[168:169], v[150:151], 0, s[34:35]
	s_mov_b64 s[34:35], 0x2080
	v_lshl_add_u64 v[170:171], v[150:151], 0, s[34:35]
	s_mov_b64 s[34:35], 0x2880
	v_lshl_add_u64 v[172:173], v[150:151], 0, s[34:35]
	s_mov_b64 s[34:35], 0x3080
	v_lshl_add_u64 v[174:175], v[150:151], 0, s[34:35]
	s_mov_b64 s[34:35], 0x3880
	v_lshl_add_u64 v[176:177], v[150:151], 0, s[34:35]
	s_mov_b64 s[34:35], 0x4000
	v_lshl_add_u64 v[178:179], v[150:151], 0, s[34:35]
	s_mov_b64 s[34:35], 0x1100
	v_lshl_add_u64 v[180:181], v[152:153], 0, s[34:35]
	s_mov_b64 s[34:35], 0x1900
	v_lshrrev_b32_e32 v4, 1, v146
	v_lshrrev_b32_e32 v5, 1, v144
	v_lshrrev_b32_e32 v6, 1, v210
	v_lshrrev_b32_e32 v7, 1, v211
	v_lshl_add_u64 v[182:183], v[152:153], 0, s[34:35]
	s_mov_b64 s[34:35], 0x2100
	v_and_b32_e32 v0, 0x80, v10
	v_xor_b32_e32 v4, v4, v207
	v_xor_b32_e32 v5, v5, v207
	v_xor_b32_e32 v6, v6, v207
	v_xor_b32_e32 v7, v7, v207
	v_xor_b32_e32 v11, v205, v207
	v_lshl_add_u64 v[184:185], v[152:153], 0, s[34:35]
	s_mov_b64 s[34:35], 0x2900
	v_add_u32_e32 v0, s33, v0
	v_lshlrev_b32_e32 v3, 4, v3
	v_lshlrev_b32_e32 v4, 4, v4
	v_lshlrev_b32_e32 v5, 4, v5
	v_lshlrev_b32_e32 v6, 4, v6
	v_lshlrev_b32_e32 v7, 4, v7
	v_lshlrev_b32_e32 v9, 4, v9
	v_lshlrev_b32_e32 v11, 4, v11
	v_lshl_add_u64 v[186:187], v[152:153], 0, s[34:35]
	s_mov_b64 s[34:35], 0x3100
	v_lshl_add_u32 v1, v192, 8, s33
	v_and_b32_e32 v2, 0xffffffe0, v207
	v_and_b32_e32 v3, 0x70, v3
	v_and_b32_e32 v4, 0x70, v4
	v_and_b32_e32 v5, 0x70, v5
	v_and_b32_e32 v6, 0x70, v6
	v_and_b32_e32 v7, 0x70, v7
	v_lshl_add_u32 v8, v213, 8, v0
	v_and_b32_e32 v9, 0x70, v9
	v_lshl_add_u32 v10, v205, 8, v0
	v_and_b32_e32 v11, 0x70, v11
	v_lshl_add_u32 v12, v202, 8, v0
	v_lshl_add_u32 v13, v201, 8, v0
	v_lshl_add_u32 v15, v200, 8, v0
	v_lshl_add_u32 v16, v199, 8, v0
	v_lshl_add_u32 v18, v145, 8, v0
	v_lshl_add_u32 v0, v147, 8, v0
	v_lshl_add_u64 v[188:189], v[152:153], 0, s[34:35]
	s_mov_b64 s[34:35], 0x3900
	v_lshl_add_u32 v24, v146, 7, s33
	v_lshl_add_u32 v25, v144, 7, s33
	v_lshl_add_u32 v26, v210, 7, s33
	v_lshl_add_u32 v27, v211, 7, s33
	v_and_b32_e32 v29, 0x70, v28
	v_and_b32_e32 v30, 0x70, v30
	v_bitop3_b32 v28, v28, 64, v197 bitop3:0x6c
	v_and_b32_e32 v31, 0x70, v31
	v_mov_b32_e32 v48, 0
	s_cselect_b32 s25, 1, 2
	v_lshl_add_u64 v[190:191], v[152:153], 0, s[34:35]
	v_add_u32_e32 v144, s55, v2
	v_add_u32_e32 v146, v8, v9
	v_add_u32_e32 v206, v10, v11
	v_add_u32_e32 v207, v12, v9
	v_add_u32_e32 v208, v13, v14
	v_add_u32_e32 v209, v15, v9
	v_add_u32_e32 v210, v16, v17
	v_add_u32_e32 v211, v18, v9
	v_add_u32_e32 v212, v0, v19
	v_add_u32_e32 v214, v1, v20
	v_add_u32_e32 v215, v1, v21
	v_add_u32_e32 v216, v1, v22
	v_add_u32_e32 v217, v1, v23
	v_add_u32_e32 v204, v204, v3
	v_add_u32_e32 v218, v24, v4
	v_add_u32_e32 v219, v25, v5
	v_add_u32_e32 v220, v26, v6
	v_add_u32_e32 v221, v27, v7
	v_add_u32_e32 v222, v203, v29
	v_add_u32_e32 v223, v203, v30
	v_add_u32_e32 v224, v203, v28
	v_add_u32_e32 v203, v203, v31
	s_mov_b32 s39, s8
	v_mov_b32_e32 v49, v48
	v_mov_b32_e32 v50, v48
	v_mov_b32_e32 v51, v48
	v_mov_b32_e32 v52, v48
	v_mov_b32_e32 v53, v48
	v_mov_b32_e32 v54, v48
	v_mov_b32_e32 v55, v48
	v_mov_b32_e32 v56, v48
	v_mov_b32_e32 v57, v48
	v_mov_b32_e32 v58, v48
	v_mov_b32_e32 v59, v48
	v_mov_b32_e32 v60, v48
	v_mov_b32_e32 v61, v48
	v_mov_b32_e32 v62, v48
	v_mov_b32_e32 v63, v48
	v_mov_b32_e32 v32, v48
	v_mov_b32_e32 v33, v48
	v_mov_b32_e32 v34, v48
	v_mov_b32_e32 v35, v48
	v_mov_b32_e32 v36, v48
	v_mov_b32_e32 v37, v48
	v_mov_b32_e32 v38, v48
	v_mov_b32_e32 v39, v48
	v_mov_b32_e32 v40, v48
	v_mov_b32_e32 v41, v48
	v_mov_b32_e32 v42, v48
	v_mov_b32_e32 v43, v48
	v_mov_b32_e32 v44, v48
	v_mov_b32_e32 v45, v48
	v_mov_b32_e32 v46, v48
	v_mov_b32_e32 v47, v48
	v_mov_b32_e32 v16, v48
	v_mov_b32_e32 v17, v48
	v_mov_b32_e32 v18, v48
	v_mov_b32_e32 v19, v48
	v_mov_b32_e32 v20, v48
	v_mov_b32_e32 v21, v48
	v_mov_b32_e32 v22, v48
	v_mov_b32_e32 v23, v48
	v_mov_b32_e32 v24, v48
	v_mov_b32_e32 v25, v48
	v_mov_b32_e32 v26, v48
	v_mov_b32_e32 v27, v48
	v_mov_b32_e32 v28, v48
	v_mov_b32_e32 v29, v48
	v_mov_b32_e32 v30, v48
	v_mov_b32_e32 v31, v48
	v_mov_b32_e32 v0, v48
	v_mov_b32_e32 v1, v48
	v_mov_b32_e32 v2, v48
	v_mov_b32_e32 v3, v48
	v_mov_b32_e32 v4, v48
	v_mov_b32_e32 v5, v48
	v_mov_b32_e32 v6, v48
	v_mov_b32_e32 v7, v48
	v_mov_b32_e32 v8, v48
	v_mov_b32_e32 v9, v48
	v_mov_b32_e32 v10, v48
	v_mov_b32_e32 v11, v48
	v_mov_b32_e32 v12, v48
	v_mov_b32_e32 v13, v48
	v_mov_b32_e32 v14, v48
	v_mov_b32_e32 v15, v48
	s_branch .LBB0_225
